# conv pass P8: software-pipelined row loads one iteration ahead into spare VGPRs (on top of K swizzle + counted PV waits)
# baseline (speedup 1.0000x reference)
; DEVFI unsigned cvt_pk_bf16(float lo, float hi) { unsigned r; asm volatile("v_cvt_pk_bf16_f32 %0, %1, %2" : "=v"(r) : "v"(lo), "v"(hi)); return r; }
; __global__ void __launch_bounds__(512, 2) mega(Args args) {
;     ...
;                     const bf16_t* hp = Hb + (size_t)r0 * FF2 + c;
;                     const u32x4 zero = {0u, 0u, 0u, 0u};
;                     u32x4 pa = zero, pg = zero, ca, cg2, na, ng;
;                     if ((r0 & (S - 1)) != 0) { pa = *(const u32x4*)(hp - FF2); pg = *(const u32x4*)(hp - FF2 + DFF); }
;                     ca = *(const u32x4*)hp; cg2 = *(const u32x4*)(hp + DFF);
;                     const bool endseq = ((r0 + RB) & (S - 1)) == 0;
;                     for (int ib = 0; ib < RB; ib += 4) {
;                         u32x4 nA[4], nG[4];
; #pragma unroll
;                         for (int k = 0; k < 4; ++k) { const int i = ib + k;
;                             if (i < RB - 1 || !endseq) { nA[k] = *(const u32x4*)(hp + (size_t)(i + 1) * FF2); nG[k] = *(const u32x4*)(hp + (size_t)(i + 1) * FF2 + DFF); } else { nA[k] = zero; nG[k] = zero; } }
; #pragma unroll
;                         for (int kk = 0; kk < 4; ++kk) { const int i = ib + kk; na = nA[kk]; ng = nG[kk];
;                             float o[8];
; #pragma unroll
;                             for (int k = 0; k < 4; ++k) {
;                                 const unsigned p0 = pa[k], c0 = ca[k], n0 = na[k], p1 = pg[k], c1 = cg2[k], n1 = ng[k];
;                                 const float a_lo = ba[2 * k] + bflo(p0) * wa[0][2 * k] + bflo(c0) * wa[1][2 * k] + bflo(n0) * wa[2][2 * k];
;                                 const float a_hi = ba[2 * k + 1] + bfhi(p0) * wa[0][2 * k + 1] + bfhi(c0) * wa[1][2 * k + 1] + bfhi(n0) * wa[2][2 * k + 1];
;                                 const float g_lo = bg[2 * k] + bflo(p1) * wg[0][2 * k] + bflo(c1) * wg[1][2 * k] + bflo(n1) * wg[2][2 * k];
;                                 const float g_hi = bg[2 * k + 1] + bfhi(p1) * wg[0][2 * k + 1] + bfhi(c1) * wg[1][2 * k + 1] + bfhi(n1) * wg[2][2 * k + 1];
;                                 o[2 * k] = silu(a_lo) * g_lo; o[2 * k + 1] = silu(a_hi) * g_hi;
;                             }
;                             u32x4 w; w.x = cvt_pk_bf16(o[0], o[1]); w.y = cvt_pk_bf16(o[2], o[3]); w.z = cvt_pk_bf16(o[4], o[5]); w.w = cvt_pk_bf16(o[6], o[7]);
.LBB0_1599:
	s_or_b64 exec, exec, s[0:1]
	v_add_co_u32_e32 v14, vcc, 0x1000, v72
	v_add_u32_e32 v13, 32, v93
	s_nop 0
	v_addc_co_u32_e32 v15, vcc, 0, v73, vcc
	global_load_dwordx4 v[88:91], v[72:73], off
	global_load_dwordx4 v[84:87], v[14:15], off offset:1536
	v_and_b32_e32 v13, s77, v13
	v_cmp_eq_u32_e32 vcc, 0, v13
	s_waitcnt vmcnt(16)
	v_mov_b32_e32 v116, v2
	v_mov_b32_e32 v124, v0
	s_waitcnt vmcnt(14)
	v_mov_b32_e32 v125, v36
	v_mov_b32_e32 v36, v1
	v_add3_u32 v2, v75, v74, v92
	v_mov_b64_e32 v[0:1], s[10:11]
	s_mov_b32 s0, 0x2c000
	s_waitcnt vmcnt(5)
	v_mov_b32_e32 v98, v66
	s_waitcnt vmcnt(3)
	v_mov_b32_e32 v99, v58
	v_mov_b32_e32 v100, v22
	v_mov_b32_e32 v101, v34
	v_mov_b32_e32 v102, v26
	v_mov_b32_e32 v103, v42
	v_mov_b32_e32 v104, v30
	v_mov_b32_e32 v105, v50
	v_mov_b32_e32 v58, v67
	v_mov_b32_e32 v34, v23
	v_mov_b32_e32 v42, v27
	v_mov_b32_e32 v50, v31
	v_mov_b32_e32 v106, v64
	v_mov_b32_e32 v107, v56
	v_mov_b32_e32 v108, v20
	v_mov_b32_e32 v109, v32
	v_mov_b32_e32 v110, v24
	v_mov_b32_e32 v111, v40
	v_mov_b32_e32 v112, v28
	v_mov_b32_e32 v113, v48
	v_mov_b32_e32 v56, v65
	v_mov_b32_e32 v32, v21
	v_mov_b32_e32 v40, v25
	v_mov_b32_e32 v48, v29
	v_mov_b32_e32 v114, v18
	s_waitcnt vmcnt(2)
	v_mov_b32_e32 v115, v62
	v_mov_b32_e32 v117, v38
	v_mov_b32_e32 v118, v6
	v_mov_b32_e32 v119, v46
	v_mov_b32_e32 v120, v10
	v_mov_b32_e32 v121, v54
	v_mov_b32_e32 v62, v19
	v_mov_b32_e32 v38, v3
	v_mov_b32_e32 v46, v7
	v_mov_b32_e32 v54, v11
	v_mov_b32_e32 v122, v16
	v_mov_b32_e32 v123, v60
	v_mov_b32_e32 v126, v4
	v_mov_b32_e32 v127, v44
	v_mov_b32_e32 v128, v8
	v_mov_b32_e32 v129, v52
	v_mov_b32_e32 v60, v17
	v_mov_b32_e32 v44, v5
	v_mov_b32_e32 v52, v9
	v_lshlrev_b64 v[130:131], 1, v[68:69]
	v_mad_u64_u32 v[132:133], s[0:1], v2, s0, v[0:1]
	v_lshl_add_u64 v[134:135], s[10:11], 0, v[70:71]
	s_mov_b32 s36, 3
	s_xor_b64 s[34:35], vcc, -1
	v_lshl_add_u64 v[178:179], v[134:135], 0, v[130:131]
	s_cmp_lt_u32 s36, 31
	s_cselect_b64 s[0:1], -1, 0
	s_or_b64 s[0:1], s[0:1], s[34:35]
	v_add_co_u32_e32 v180, vcc, 0x12c02000, v178
	s_nop 1
	v_addc_co_u32_e32 v181, vcc, 0, v179, vcc
	global_load_dwordx4 v[146:149], v[180:181], off offset:3072
	v_add_co_u32_e32 v180, vcc, 0x12c04000, v178
	s_nop 1
	v_addc_co_u32_e32 v181, vcc, 0, v179, vcc
	global_load_dwordx4 v[150:153], v[180:181], off offset:512
	v_add_co_u32_e32 v180, vcc, 0x12c05000, v178
	s_nop 1
	v_addc_co_u32_e32 v181, vcc, 0, v179, vcc
	global_load_dwordx4 v[154:157], v[180:181], off offset:2048
	v_add_co_u32_e32 v180, vcc, 0x12c06000, v178
	s_nop 1
	v_addc_co_u32_e32 v181, vcc, 0, v179, vcc
	global_load_dwordx4 v[158:161], v[180:181], off offset:3584
	v_add_co_u32_e32 v180, vcc, 0x12c08000, v178
	s_nop 1
	v_addc_co_u32_e32 v181, vcc, 0, v179, vcc
	global_load_dwordx4 v[162:165], v[180:181], off offset:1024
	v_add_co_u32_e32 v180, vcc, 0x12c09000, v178
	s_nop 1
	v_addc_co_u32_e32 v181, vcc, 0, v179, vcc
	global_load_dwordx4 v[166:169], v[180:181], off offset:2560
	v_mov_b32_e32 v170, v12
	v_mov_b32_e32 v171, v12
	v_mov_b32_e32 v172, v12
	v_mov_b32_e32 v173, v12
	v_mov_b32_e32 v174, v12
	v_mov_b32_e32 v175, v12
	v_mov_b32_e32 v176, v12
	v_mov_b32_e32 v177, v12
	s_and_saveexec_b64 s[38:39], s[0:1]
	s_cbranch_execz .Lp8_skipA
	v_add_co_u32_e32 v180, vcc, 0x12c0b000, v178
	s_nop 1
	v_addc_co_u32_e32 v181, vcc, 0, v179, vcc
	global_load_dwordx4 v[170:173], v[180:181], off
	v_add_co_u32_e32 v180, vcc, 0x12c0c000, v178
	s_nop 1
	v_addc_co_u32_e32 v181, vcc, 0, v179, vcc
	global_load_dwordx4 v[174:177], v[180:181], off offset:1536
.Lp8_skipA:
	s_mov_b64 exec, s[38:39]
	s_waitcnt vmcnt(0)
	s_branch .Lp8_land
.Lp8_compute:
	v_lshlrev_b32_e32 v0, 16, v76
	v_lshlrev_b32_e32 v1, 16, v80
	v_pk_fma_f32 v[0:1], v[124:125], v[0:1], v[122:123]
	v_lshlrev_b32_e32 v136, 16, v88
	v_lshlrev_b32_e32 v137, 16, v84
	v_pk_fma_f32 v[0:1], v[126:127], v[136:137], v[0:1]
	v_lshlrev_b32_e32 v3, 16, v92
	v_lshlrev_b32_e32 v2, 16, v16
	v_pk_fma_f32 v[0:1], v[128:129], v[2:3], v[0:1]
	v_and_b32_e32 v5, 0xffff0000, v80
	v_mul_f32_e32 v8, 0xbfb8aa3b, v0
	v_exp_f32_e32 v8, v8
	v_and_b32_e32 v4, 0xffff0000, v76
	v_pk_fma_f32 v[4:5], v[36:37], v[4:5], v[60:61]
	v_and_b32_e32 v139, 0xffff0000, v84
	v_add_f32_e32 v8, 1.0, v8
	v_rcp_f32_e32 v8, v8
	v_and_b32_e32 v138, 0xffff0000, v88
	v_pk_fma_f32 v[6:7], v[44:45], v[138:139], v[4:5]
	v_and_b32_e32 v5, 0xffff0000, v92
	v_and_b32_e32 v4, 0xffff0000, v16
	v_pk_fma_f32 v[6:7], v[52:53], v[4:5], v[6:7]
	v_mul_f32_e32 v0, v0, v8
	v_mul_f32_e32 v13, v0, v1
	v_mul_f32_e32 v0, 0xbfb8aa3b, v6
	v_exp_f32_e32 v0, v0
	v_lshlrev_b32_e32 v1, 16, v81
	v_lshlrev_b32_e32 v140, 16, v89
	v_lshlrev_b32_e32 v141, 16, v85
	v_add_f32_e32 v0, 1.0, v0
	v_rcp_f32_e32 v0, v0
	v_and_b32_e32 v9, 0xffff0000, v81
	v_and_b32_e32 v8, 0xffff0000, v77
	v_pk_fma_f32 v[8:9], v[38:39], v[8:9], v[62:63]
	v_mul_f32_e32 v0, v6, v0
	v_mul_f32_e32 v84, v0, v7
	v_lshlrev_b32_e32 v0, 16, v77
	v_pk_fma_f32 v[0:1], v[116:117], v[0:1], v[114:115]
	v_lshlrev_b32_e32 v7, 16, v93
	v_pk_fma_f32 v[0:1], v[118:119], v[140:141], v[0:1]
	v_lshlrev_b32_e32 v6, 16, v17
	v_pk_fma_f32 v[0:1], v[120:121], v[6:7], v[0:1]
	v_and_b32_e32 v81, 0xffff0000, v85
	v_mul_f32_e32 v14, 0xbfb8aa3b, v0
	v_exp_f32_e32 v14, v14
	v_and_b32_e32 v80, 0xffff0000, v89
	v_pk_fma_f32 v[10:11], v[46:47], v[80:81], v[8:9]
	v_and_b32_e32 v9, 0xffff0000, v93
	v_add_f32_e32 v14, 1.0, v14
	v_rcp_f32_e32 v14, v14
	v_and_b32_e32 v8, 0xffff0000, v17
	v_pk_fma_f32 v[10:11], v[54:55], v[8:9], v[10:11]
	v_lshlrev_b32_e32 v88, 16, v90
	v_mul_f32_e32 v0, v0, v14
	v_mul_f32_e32 v85, v0, v1
	v_mul_f32_e32 v0, 0xbfb8aa3b, v10
	v_exp_f32_e32 v0, v0
	v_lshlrev_b32_e32 v1, 16, v82
; DEVFI unsigned cvt_pk_bf16(float lo, float hi) { unsigned r; asm volatile("v_cvt_pk_bf16_f32 %0, %1, %2" : "=v"(r) : "v"(lo), "v"(hi)); return r; }
; DEVFI float silu(float x) { return x * fast_sigmoid(x); }
; __global__ void __launch_bounds__(512, 2) mega(Args args) {
;     ...
;                         for (int kk = 0; kk < 4; ++kk) { const int i = ib + kk; na = nA[kk]; ng = nG[kk];
;                             float o[8];
; #pragma unroll
;                             for (int k = 0; k < 4; ++k) {
;                                 const unsigned p0 = pa[k], c0 = ca[k], n0 = na[k], p1 = pg[k], c1 = cg2[k], n1 = ng[k];
;                                 const float a_lo = ba[2 * k] + bflo(p0) * wa[0][2 * k] + bflo(c0) * wa[1][2 * k] + bflo(n0) * wa[2][2 * k];
;                                 const float a_hi = ba[2 * k + 1] + bfhi(p0) * wa[0][2 * k + 1] + bfhi(c0) * wa[1][2 * k + 1] + bfhi(n0) * wa[2][2 * k + 1];
;                                 const float g_lo = bg[2 * k] + bflo(p1) * wg[0][2 * k] + bflo(c1) * wg[1][2 * k] + bflo(n1) * wg[2][2 * k];
;                                 const float g_hi = bg[2 * k + 1] + bfhi(p1) * wg[0][2 * k + 1] + bfhi(c1) * wg[1][2 * k + 1] + bfhi(n1) * wg[2][2 * k + 1];
;                                 o[2 * k] = silu(a_lo) * g_lo; o[2 * k + 1] = silu(a_hi) * g_hi;
;                             }
;                             u32x4 w; w.x = cvt_pk_bf16(o[0], o[1]); w.y = cvt_pk_bf16(o[2], o[3]); w.z = cvt_pk_bf16(o[4], o[5]); w.w = cvt_pk_bf16(o[6], o[7]);
;                             *(u32x4*)(ACT + (size_t)(r0 + i) * DFF + c) = w;
	v_lshlrev_b32_e32 v89, 16, v86
	v_and_b32_e32 v15, 0xffff0000, v82
	v_add_f32_e32 v0, 1.0, v0
	v_rcp_f32_e32 v0, v0
	v_and_b32_e32 v14, 0xffff0000, v78
	v_pk_fma_f32 v[14:15], v[32:33], v[14:15], v[56:57]
	v_and_b32_e32 v93, 0xffff0000, v86
	v_mul_f32_e32 v0, v10, v0
	v_mul_f32_e32 v144, v0, v11
	v_lshlrev_b32_e32 v0, 16, v78
	v_pk_fma_f32 v[0:1], v[108:109], v[0:1], v[106:107]
	v_lshlrev_b32_e32 v11, 16, v94
	v_pk_fma_f32 v[0:1], v[110:111], v[88:89], v[0:1]
	v_lshlrev_b32_e32 v10, 16, v18
	v_pk_fma_f32 v[0:1], v[112:113], v[10:11], v[0:1]
	v_and_b32_e32 v92, 0xffff0000, v90
	v_pk_fma_f32 v[16:17], v[40:41], v[92:93], v[14:15]
	v_and_b32_e32 v14, 0xffff0000, v18
	v_mul_f32_e32 v18, 0xbfb8aa3b, v0
	v_exp_f32_e32 v18, v18
	v_and_b32_e32 v15, 0xffff0000, v94
	v_pk_fma_f32 v[16:17], v[48:49], v[14:15], v[16:17]
	v_lshlrev_b32_e32 v142, 16, v91
	v_add_f32_e32 v18, 1.0, v18
	v_rcp_f32_e32 v18, v18
	v_lshlrev_b32_e32 v143, 16, v87
	v_and_b32_e32 v77, 0xffff0000, v83
	v_and_b32_e32 v76, 0xffff0000, v79
	v_mul_f32_e32 v0, v0, v18
	v_mul_f32_e32 v90, v0, v1
	v_mul_f32_e32 v0, 0xbfb8aa3b, v16
	v_exp_f32_e32 v0, v0
	v_lshlrev_b32_e32 v1, 16, v83
	v_pk_fma_f32 v[76:77], v[34:35], v[76:77], v[58:59]
	v_and_b32_e32 v87, 0xffff0000, v87
	v_add_f32_e32 v0, 1.0, v0
	v_rcp_f32_e32 v0, v0
	v_and_b32_e32 v86, 0xffff0000, v91
	v_cvt_pk_bf16_f32 v82, v13, v84
	v_cvt_pk_bf16_f32 v83, v85, v144
	v_mul_f32_e32 v0, v16, v0
	v_mul_f32_e32 v94, v0, v17
	v_lshlrev_b32_e32 v0, 16, v79
	v_pk_fma_f32 v[0:1], v[100:101], v[0:1], v[98:99]
	v_lshlrev_b32_e32 v17, 16, v95
	v_pk_fma_f32 v[0:1], v[102:103], v[142:143], v[0:1]
	v_lshlrev_b32_e32 v16, 16, v19
	v_pk_fma_f32 v[0:1], v[104:105], v[16:17], v[0:1]
	v_pk_fma_f32 v[78:79], v[42:43], v[86:87], v[76:77]
	v_and_b32_e32 v77, 0xffff0000, v95
	v_and_b32_e32 v76, 0xffff0000, v19
	v_pk_fma_f32 v[18:19], v[50:51], v[76:77], v[78:79]
	v_mul_f32_e32 v78, 0xbfb8aa3b, v0
	v_exp_f32_e32 v78, v78
	v_cvt_pk_bf16_f32 v84, v90, v94
	s_mov_b32 s0, 0x28c00000
	v_pk_fma_f32 v[80:81], v[38:39], v[80:81], v[62:63]
	v_add_f32_e32 v78, 1.0, v78
	v_rcp_f32_e32 v78, v78
	v_pk_fma_f32 v[80:81], v[46:47], v[8:9], v[80:81]
	v_pk_fma_f32 v[86:87], v[34:35], v[86:87], v[58:59]
	v_mul_f32_e32 v0, v0, v78
	v_mul_f32_e32 v0, v0, v1
	v_mul_f32_e32 v1, 0xbfb8aa3b, v18
	v_exp_f32_e32 v1, v1
	v_pk_fma_f32 v[86:87], v[42:43], v[76:77], v[86:87]
	v_add_f32_e32 v1, 1.0, v1
	v_rcp_f32_e32 v1, v1
	s_nop 0
	v_mul_f32_e32 v1, v18, v1
	v_mul_f32_e32 v1, v1, v19
	v_cvt_pk_bf16_f32 v85, v0, v1
	v_lshl_add_u64 v[0:1], v[132:133], 0, v[130:131]
	v_add_co_u32_e32 v18, vcc, s0, v0
	s_mov_b32 s0, 0x28c01000
	s_nop 0
	v_addc_co_u32_e32 v19, vcc, 0, v1, vcc
	global_store_dwordx4 v[18:19], v[82:85], off
	v_pk_fma_f32 v[18:19], v[124:125], v[136:137], v[122:123]
	s_nop 0
	v_pk_fma_f32 v[18:19], v[126:127], v[2:3], v[18:19]
	v_lshlrev_b32_e32 v85, 16, v72
	v_lshlrev_b32_e32 v84, 16, v20
	v_pk_fma_f32 v[78:79], v[128:129], v[84:85], v[18:19]
	v_pk_fma_f32 v[18:19], v[36:37], v[138:139], v[60:61]
	v_mul_f32_e32 v13, 0xbfb8aa3b, v78
	v_pk_fma_f32 v[82:83], v[44:45], v[4:5], v[18:19]
	v_and_b32_e32 v19, 0xffff0000, v72
	v_and_b32_e32 v18, 0xffff0000, v20
	v_pk_fma_f32 v[82:83], v[52:53], v[18:19], v[82:83]
	v_exp_f32_e32 v13, v13
	v_mul_f32_e32 v20, 0xbfb8aa3b, v82
	v_exp_f32_e32 v20, v20
	v_and_b32_e32 v72, 0xffff0000, v21
	v_add_f32_e32 v13, 1.0, v13
	v_rcp_f32_e32 v13, v13
	v_add_f32_e32 v20, 1.0, v20
	v_rcp_f32_e32 v20, v20
	v_pk_fma_f32 v[2:3], v[124:125], v[2:3], v[122:123]
	v_mul_f32_e32 v13, v78, v13
	v_mul_f32_e32 v13, v13, v79
	v_mul_f32_e32 v20, v82, v20
	v_pk_fma_f32 v[78:79], v[116:117], v[140:141], v[114:115]
	v_mul_f32_e32 v90, v20, v83
	v_pk_fma_f32 v[78:79], v[118:119], v[6:7], v[78:79]
	v_lshlrev_b32_e32 v83, 16, v73
	v_lshlrev_b32_e32 v82, 16, v21
	v_pk_fma_f32 v[78:79], v[120:121], v[82:83], v[78:79]
	v_and_b32_e32 v73, 0xffff0000, v73
	v_pk_fma_f32 v[20:21], v[54:55], v[72:73], v[80:81]
	v_mul_f32_e32 v80, 0xbfb8aa3b, v78
	v_exp_f32_e32 v80, v80
	v_lshlrev_b32_e32 v81, 16, v74
	v_pk_fma_f32 v[2:3], v[126:127], v[84:85], v[2:3]
	v_add_f32_e32 v80, 1.0, v80
	v_rcp_f32_e32 v80, v80
	s_nop 0
	v_mul_f32_e32 v78, v78, v80
	v_mul_f32_e32 v91, v78, v79
	v_mul_f32_e32 v78, 0xbfb8aa3b, v20
	v_exp_f32_e32 v78, v78
	v_lshlrev_b32_e32 v80, 16, v22
	v_add_f32_e32 v78, 1.0, v78
	v_rcp_f32_e32 v78, v78
	s_nop 0
	v_mul_f32_e32 v20, v20, v78
	v_mul_f32_e32 v94, v20, v21
	v_pk_fma_f32 v[20:21], v[108:109], v[88:89], v[106:107]
	s_nop 0
	v_pk_fma_f32 v[20:21], v[110:111], v[10:11], v[20:21]
	s_nop 0
	v_pk_fma_f32 v[78:79], v[112:113], v[80:81], v[20:21]
	v_pk_fma_f32 v[20:21], v[32:33], v[92:93], v[56:57]
	s_nop 0
	v_pk_fma_f32 v[88:89], v[40:41], v[14:15], v[20:21]
	v_and_b32_e32 v20, 0xffff0000, v22
	v_mul_f32_e32 v22, 0xbfb8aa3b, v78
	v_exp_f32_e32 v22, v22
	v_and_b32_e32 v21, 0xffff0000, v74
	v_pk_fma_f32 v[88:89], v[48:49], v[20:21], v[88:89]
	v_and_b32_e32 v74, 0xffff0000, v23
	v_add_f32_e32 v22, 1.0, v22
	v_rcp_f32_e32 v22, v22
	s_nop 0
	v_mul_f32_e32 v22, v78, v22
	v_mul_f32_e32 v92, v22, v79
	v_mul_f32_e32 v22, 0xbfb8aa3b, v88
	v_exp_f32_e32 v22, v22
	v_pk_fma_f32 v[78:79], v[100:101], v[142:143], v[98:99]
	v_add_f32_e32 v22, 1.0, v22
	v_rcp_f32_e32 v22, v22
	s_nop 0
	v_mul_f32_e32 v22, v88, v22
	v_mul_f32_e32 v93, v22, v89
	v_pk_fma_f32 v[88:89], v[102:103], v[16:17], v[78:79]
	v_lshlrev_b32_e32 v79, 16, v75
	v_lshlrev_b32_e32 v78, 16, v23
	v_pk_fma_f32 v[88:89], v[104:105], v[78:79], v[88:89]
	v_and_b32_e32 v75, 0xffff0000, v75
	v_pk_fma_f32 v[22:23], v[50:51], v[74:75], v[86:87]
	v_mul_f32_e32 v86, 0xbfb8aa3b, v88
	v_exp_f32_e32 v86, v86
	s_nop 0
	v_add_f32_e32 v86, 1.0, v86
; DEVFI unsigned cvt_pk_bf16(float lo, float hi) { unsigned r; asm volatile("v_cvt_pk_bf16_f32 %0, %1, %2" : "=v"(r) : "v"(lo), "v"(hi)); return r; }
; DEVFI float silu(float x) { return x * fast_sigmoid(x); }
; __global__ void __launch_bounds__(512, 2) mega(Args args) {
;     ...
;                         for (int kk = 0; kk < 4; ++kk) { const int i = ib + kk; na = nA[kk]; ng = nG[kk];
;                             float o[8];
; #pragma unroll
;                             for (int k = 0; k < 4; ++k) {
;                                 const unsigned p0 = pa[k], c0 = ca[k], n0 = na[k], p1 = pg[k], c1 = cg2[k], n1 = ng[k];
;                                 const float a_lo = ba[2 * k] + bflo(p0) * wa[0][2 * k] + bflo(c0) * wa[1][2 * k] + bflo(n0) * wa[2][2 * k];
;                                 const float a_hi = ba[2 * k + 1] + bfhi(p0) * wa[0][2 * k + 1] + bfhi(c0) * wa[1][2 * k + 1] + bfhi(n0) * wa[2][2 * k + 1];
;                                 const float g_lo = bg[2 * k] + bflo(p1) * wg[0][2 * k] + bflo(c1) * wg[1][2 * k] + bflo(n1) * wg[2][2 * k];
;                                 const float g_hi = bg[2 * k + 1] + bfhi(p1) * wg[0][2 * k + 1] + bfhi(c1) * wg[1][2 * k + 1] + bfhi(n1) * wg[2][2 * k + 1];
;                                 o[2 * k] = silu(a_lo) * g_lo; o[2 * k + 1] = silu(a_hi) * g_hi;
;                             }
;                             u32x4 w; w.x = cvt_pk_bf16(o[0], o[1]); w.y = cvt_pk_bf16(o[2], o[3]); w.z = cvt_pk_bf16(o[4], o[5]); w.w = cvt_pk_bf16(o[6], o[7]);
;                             *(u32x4*)(ACT + (size_t)(r0 + i) * DFF + c) = w;
	v_rcp_f32_e32 v86, v86
	s_nop 0
	v_mul_f32_e32 v86, v88, v86
	v_mul_f32_e32 v89, v86, v89
	v_mul_f32_e32 v86, 0xbfb8aa3b, v22
	v_exp_f32_e32 v86, v86
	s_nop 0
	v_add_f32_e32 v86, 1.0, v86
	v_rcp_f32_e32 v86, v86
	s_nop 0
	v_mul_f32_e32 v22, v22, v86
	v_mul_f32_e32 v22, v22, v23
	v_cvt_pk_bf16_f32 v86, v13, v90
	v_cvt_pk_bf16_f32 v87, v91, v94
	v_cvt_pk_bf16_f32 v88, v92, v93
	v_cvt_pk_bf16_f32 v89, v89, v22
	v_add_co_u32_e32 v22, vcc, s0, v0
	s_mov_b32 s0, 0x28c02000
	s_nop 0
	v_addc_co_u32_e32 v23, vcc, 0, v1, vcc
	global_store_dwordx4 v[22:23], v[86:89], off offset:1536
	s_nop 0
	s_nop 0
	v_lshlrev_b32_e32 v89, 16, v64
	v_lshlrev_b32_e32 v88, 16, v24
	v_pk_fma_f32 v[22:23], v[128:129], v[88:89], v[2:3]
	v_pk_fma_f32 v[2:3], v[36:37], v[4:5], v[60:61]
	v_mul_f32_e32 v13, 0xbfb8aa3b, v22
	v_exp_f32_e32 v13, v13
	v_pk_fma_f32 v[4:5], v[44:45], v[18:19], v[2:3]
	v_and_b32_e32 v3, 0xffff0000, v64
	v_and_b32_e32 v2, 0xffff0000, v24
	v_add_f32_e32 v13, 1.0, v13
	v_rcp_f32_e32 v13, v13
	v_pk_fma_f32 v[4:5], v[52:53], v[2:3], v[4:5]
	v_lshlrev_b32_e32 v87, 16, v65
	v_lshlrev_b32_e32 v86, 16, v25
	v_mul_f32_e32 v13, v22, v13
	v_mul_f32_e32 v22, 0xbfb8aa3b, v4
	v_exp_f32_e32 v22, v22
	v_mul_f32_e32 v13, v13, v23
	v_lshlrev_b32_e32 v23, 16, v66
	v_add_f32_e32 v22, 1.0, v22
	v_rcp_f32_e32 v22, v22
	s_nop 0
	v_mul_f32_e32 v4, v4, v22
	v_mul_f32_e32 v90, v4, v5
	v_pk_fma_f32 v[4:5], v[116:117], v[6:7], v[114:115]
	s_nop 0
	v_pk_fma_f32 v[4:5], v[118:119], v[82:83], v[4:5]
	s_nop 0
	v_pk_fma_f32 v[6:7], v[120:121], v[86:87], v[4:5]
	v_pk_fma_f32 v[4:5], v[38:39], v[8:9], v[62:63]
	v_mul_f32_e32 v22, 0xbfb8aa3b, v6
	v_exp_f32_e32 v22, v22
	v_pk_fma_f32 v[8:9], v[46:47], v[72:73], v[4:5]
	v_and_b32_e32 v5, 0xffff0000, v65
	v_and_b32_e32 v4, 0xffff0000, v25
	v_add_f32_e32 v22, 1.0, v22
	v_rcp_f32_e32 v22, v22
	v_pk_fma_f32 v[8:9], v[54:55], v[4:5], v[8:9]
	v_mul_f32_e32 v6, v6, v22
	v_mul_f32_e32 v91, v6, v7
	v_mul_f32_e32 v6, 0xbfb8aa3b, v8
	v_exp_f32_e32 v6, v6
	v_lshlrev_b32_e32 v22, 16, v26
	v_add_f32_e32 v6, 1.0, v6
	v_rcp_f32_e32 v6, v6
	s_nop 0
	v_mul_f32_e32 v6, v8, v6
	v_mul_f32_e32 v92, v6, v9
	v_pk_fma_f32 v[6:7], v[108:109], v[10:11], v[106:107]
	s_nop 0
	v_pk_fma_f32 v[6:7], v[110:111], v[80:81], v[6:7]
	s_nop 0
	v_pk_fma_f32 v[8:9], v[112:113], v[22:23], v[6:7]
	v_pk_fma_f32 v[6:7], v[32:33], v[14:15], v[56:57]
	v_mul_f32_e32 v14, 0xbfb8aa3b, v8
	v_exp_f32_e32 v14, v14
	v_pk_fma_f32 v[10:11], v[40:41], v[20:21], v[6:7]
	v_and_b32_e32 v7, 0xffff0000, v66
	v_and_b32_e32 v6, 0xffff0000, v26
	v_add_f32_e32 v14, 1.0, v14
	v_rcp_f32_e32 v14, v14
	v_pk_fma_f32 v[10:11], v[48:49], v[6:7], v[10:11]
	v_mul_f32_e32 v8, v8, v14
	v_mul_f32_e32 v93, v8, v9
	v_mul_f32_e32 v8, 0xbfb8aa3b, v10
	v_exp_f32_e32 v8, v8
	s_nop 0
	v_add_f32_e32 v8, 1.0, v8
	v_rcp_f32_e32 v8, v8
	s_nop 0
	v_mul_f32_e32 v8, v10, v8
	v_mul_f32_e32 v94, v8, v11
	v_pk_fma_f32 v[8:9], v[100:101], v[16:17], v[98:99]
	v_lshlrev_b32_e32 v11, 16, v67
	v_pk_fma_f32 v[8:9], v[102:103], v[78:79], v[8:9]
	v_lshlrev_b32_e32 v10, 16, v27
	v_pk_fma_f32 v[14:15], v[104:105], v[10:11], v[8:9]
	v_pk_fma_f32 v[8:9], v[34:35], v[76:77], v[58:59]
	v_mul_f32_e32 v76, 0xbfb8aa3b, v14
	v_exp_f32_e32 v76, v76
	v_pk_fma_f32 v[16:17], v[42:43], v[74:75], v[8:9]
	v_and_b32_e32 v9, 0xffff0000, v67
	v_and_b32_e32 v8, 0xffff0000, v27
	v_add_f32_e32 v76, 1.0, v76
	v_rcp_f32_e32 v76, v76
	v_pk_fma_f32 v[16:17], v[50:51], v[8:9], v[16:17]
	v_mul_f32_e32 v14, v14, v76
	v_mul_f32_e32 v76, v14, v15
	v_mul_f32_e32 v14, 0xbfb8aa3b, v16
	v_exp_f32_e32 v14, v14
	s_nop 0
	v_add_f32_e32 v14, 1.0, v14
	v_rcp_f32_e32 v14, v14
	s_nop 0
	v_mul_f32_e32 v14, v16, v14
	v_mul_f32_e32 v17, v14, v17
	v_cvt_pk_bf16_f32 v14, v13, v90
	v_cvt_pk_bf16_f32 v15, v91, v92
	v_cvt_pk_bf16_f32 v16, v93, v94
	v_cvt_pk_bf16_f32 v17, v76, v17
	v_add_co_u32_e32 v76, vcc, s0, v0
	s_mov_b64 s[0:1], 0x5800
	s_nop 0
	v_addc_co_u32_e32 v77, vcc, 0, v1, vcc
	global_store_dwordx4 v[76:77], v[14:17], off offset:3072
; DEVFI unsigned cvt_pk_bf16(float lo, float hi) { unsigned r; asm volatile("v_cvt_pk_bf16_f32 %0, %1, %2" : "=v"(r) : "v"(lo), "v"(hi)); return r; }
; DEVFI float silu(float x) { return x * fast_sigmoid(x); }
; __global__ void __launch_bounds__(512, 2) mega(Args args) {
;     ...
;                         for (int kk = 0; kk < 4; ++kk) { const int i = ib + kk; na = nA[kk]; ng = nG[kk];
;                             float o[8];
; #pragma unroll
;                             for (int k = 0; k < 4; ++k) {
;                                 const unsigned p0 = pa[k], c0 = ca[k], n0 = na[k], p1 = pg[k], c1 = cg2[k], n1 = ng[k];
;                                 const float a_lo = ba[2 * k] + bflo(p0) * wa[0][2 * k] + bflo(c0) * wa[1][2 * k] + bflo(n0) * wa[2][2 * k];
;                                 const float a_hi = ba[2 * k + 1] + bfhi(p0) * wa[0][2 * k + 1] + bfhi(c0) * wa[1][2 * k + 1] + bfhi(n0) * wa[2][2 * k + 1];
;                                 const float g_lo = bg[2 * k] + bflo(p1) * wg[0][2 * k] + bflo(c1) * wg[1][2 * k] + bflo(n1) * wg[2][2 * k];
;                                 const float g_hi = bg[2 * k + 1] + bfhi(p1) * wg[0][2 * k + 1] + bfhi(c1) * wg[1][2 * k + 1] + bfhi(n1) * wg[2][2 * k + 1];
;                                 o[2 * k] = silu(a_lo) * g_lo; o[2 * k + 1] = silu(a_hi) * g_hi;
;                             }
;                             u32x4 w; w.x = cvt_pk_bf16(o[0], o[1]); w.y = cvt_pk_bf16(o[2], o[3]); w.z = cvt_pk_bf16(o[4], o[5]); w.w = cvt_pk_bf16(o[6], o[7]);
;                             *(u32x4*)(ACT + (size_t)(r0 + i) * DFF + c) = w;
;                             pa = ca; pg = cg2; ca = na; cg2 = ng;
;                         }
	v_lshl_add_u64 v[132:133], v[132:133], 0, s[0:1]
	s_mov_b64 s[0:1], 0xb000
	v_pk_fma_f32 v[14:15], v[124:125], v[84:85], v[122:123]
	v_lshlrev_b32_e32 v17, 16, v68
	v_pk_fma_f32 v[14:15], v[126:127], v[88:89], v[14:15]
	v_lshlrev_b32_e32 v16, 16, v28
	v_pk_fma_f32 v[14:15], v[128:129], v[16:17], v[14:15]
	v_pk_fma_f32 v[16:17], v[36:37], v[18:19], v[60:61]
	v_mul_f32_e32 v13, 0xbfb8aa3b, v14
	v_exp_f32_e32 v13, v13
	v_pk_fma_f32 v[2:3], v[44:45], v[2:3], v[16:17]
	v_and_b32_e32 v17, 0xffff0000, v68
	v_and_b32_e32 v16, 0xffff0000, v28
	v_add_f32_e32 v13, 1.0, v13
	v_rcp_f32_e32 v13, v13
	v_pk_fma_f32 v[2:3], v[52:53], v[16:17], v[2:3]
	v_add_co_u32_e32 v0, vcc, 0x28c04000, v0
	v_mul_f32_e32 v13, v14, v13
	v_mul_f32_e32 v14, 0xbfb8aa3b, v2
	v_exp_f32_e32 v14, v14
	v_mul_f32_e32 v13, v13, v15
	v_lshlrev_b32_e32 v15, 16, v69
	v_lshl_add_u64 v[134:135], v[134:135], 0, s[0:1]
	v_add_f32_e32 v14, 1.0, v14
	v_rcp_f32_e32 v14, v14
	s_add_i32 s0, s36, 4
	s_add_i32 s1, s36, -3
	v_addc_co_u32_e32 v1, vcc, 0, v1, vcc
	v_mul_f32_e32 v2, v2, v14
	v_mul_f32_e32 v16, v2, v3
	v_pk_fma_f32 v[2:3], v[116:117], v[82:83], v[114:115]
	v_lshlrev_b32_e32 v14, 16, v29
	v_pk_fma_f32 v[2:3], v[118:119], v[86:87], v[2:3]
	v_mov_b64_e32 v[86:87], v[70:71]
	v_pk_fma_f32 v[2:3], v[120:121], v[14:15], v[2:3]
	v_pk_fma_f32 v[14:15], v[38:39], v[72:73], v[62:63]
	s_cmp_gt_u32 s1, 27
	v_pk_fma_f32 v[4:5], v[46:47], v[4:5], v[14:15]
	v_and_b32_e32 v15, 0xffff0000, v69
	v_and_b32_e32 v14, 0xffff0000, v29
	v_pk_fma_f32 v[4:5], v[54:55], v[14:15], v[4:5]
	v_mul_f32_e32 v14, 0xbfb8aa3b, v2
	v_exp_f32_e32 v14, v14
	s_mov_b32 s36, s0
	v_mov_b64_e32 v[84:85], v[68:69]
	v_mov_b32_e32 v76, v24
	v_add_f32_e32 v14, 1.0, v14
	v_rcp_f32_e32 v14, v14
	v_mov_b32_e32 v77, v25
	v_mov_b32_e32 v88, v28
	v_mov_b32_e32 v89, v29
	v_mul_f32_e32 v2, v2, v14
	v_mul_f32_e32 v14, v2, v3
	v_mul_f32_e32 v2, 0xbfb8aa3b, v4
	v_exp_f32_e32 v2, v2
	v_mov_b32_e32 v90, v30
	v_mov_b32_e32 v91, v31
	v_add_f32_e32 v2, 1.0, v2
	v_rcp_f32_e32 v2, v2
	s_nop 0
	v_mul_f32_e32 v2, v4, v2
	v_mul_f32_e32 v15, v2, v5
	v_pk_fma_f32 v[2:3], v[108:109], v[80:81], v[106:107]
	v_lshlrev_b32_e32 v5, 16, v70
	v_pk_fma_f32 v[2:3], v[110:111], v[22:23], v[2:3]
	v_lshlrev_b32_e32 v4, 16, v30
	v_pk_fma_f32 v[2:3], v[112:113], v[4:5], v[2:3]
	v_pk_fma_f32 v[4:5], v[32:33], v[20:21], v[56:57]
	v_mov_b64_e32 v[82:83], v[66:67]
	v_pk_fma_f32 v[4:5], v[40:41], v[6:7], v[4:5]
	v_and_b32_e32 v7, 0xffff0000, v70
	v_and_b32_e32 v6, 0xffff0000, v30
	v_pk_fma_f32 v[4:5], v[48:49], v[6:7], v[4:5]
	v_mul_f32_e32 v6, 0xbfb8aa3b, v2
	v_exp_f32_e32 v6, v6
	v_and_b32_e32 v7, 0xffff0000, v71
	v_mov_b64_e32 v[80:81], v[64:65]
	v_add_f32_e32 v6, 1.0, v6
	v_rcp_f32_e32 v6, v6
	s_nop 0
	v_mul_f32_e32 v2, v2, v6
	v_mul_f32_e32 v17, v2, v3
	v_mul_f32_e32 v2, 0xbfb8aa3b, v4
	v_exp_f32_e32 v2, v2
	v_and_b32_e32 v6, 0xffff0000, v31
	v_add_f32_e32 v2, 1.0, v2
	v_rcp_f32_e32 v2, v2
	s_nop 0
	v_mul_f32_e32 v2, v4, v2
	v_mul_f32_e32 v18, v2, v5
	v_pk_fma_f32 v[2:3], v[100:101], v[78:79], v[98:99]
	v_lshlrev_b32_e32 v5, 16, v71
	v_pk_fma_f32 v[2:3], v[102:103], v[10:11], v[2:3]
	v_lshlrev_b32_e32 v4, 16, v31
	v_pk_fma_f32 v[2:3], v[104:105], v[4:5], v[2:3]
	v_pk_fma_f32 v[4:5], v[34:35], v[74:75], v[58:59]
	v_mov_b32_e32 v78, v26
	v_pk_fma_f32 v[4:5], v[42:43], v[8:9], v[4:5]
	v_mov_b32_e32 v79, v27
	v_pk_fma_f32 v[4:5], v[50:51], v[6:7], v[4:5]
	v_mul_f32_e32 v6, 0xbfb8aa3b, v2
	v_exp_f32_e32 v6, v6
	s_nop 0
	v_add_f32_e32 v6, 1.0, v6
	v_rcp_f32_e32 v6, v6
	s_nop 0
	v_mul_f32_e32 v2, v2, v6
	v_mul_f32_e32 v6, v2, v3
	v_mul_f32_e32 v2, 0xbfb8aa3b, v4
	v_exp_f32_e32 v2, v2
	s_nop 0
	v_add_f32_e32 v2, 1.0, v2
	v_rcp_f32_e32 v2, v2
	s_nop 0
	v_mul_f32_e32 v2, v4, v2
	v_mul_f32_e32 v5, v2, v5
	v_cvt_pk_bf16_f32 v2, v13, v16
	v_cvt_pk_bf16_f32 v3, v14, v15
	v_cvt_pk_bf16_f32 v4, v17, v18
	v_cvt_pk_bf16_f32 v5, v6, v5
	global_store_dwordx4 v[0:1], v[2:5], off offset:512
	s_cbranch_scc1 .LBB0_1596

; __global__ void __launch_bounds__(512, 2) mega(Args args) {
;     ...
;                     for (int ib = 0; ib < RB; ib += 4) {
;                         u32x4 nA[4], nG[4];
; #pragma unroll
;                         for (int k = 0; k < 4; ++k) { const int i = ib + k;
;                             if (i < RB - 1 || !endseq) { nA[k] = *(const u32x4*)(hp + (size_t)(i + 1) * FF2); nG[k] = *(const u32x4*)(hp + (size_t)(i + 1) * FF2 + DFF); } else { nA[k] = zero; nG[k] = zero; } }
.Lp8_land:
	v_mov_b64_e32 v[16:17], v[146:147]
	v_mov_b64_e32 v[18:19], v[148:149]
	v_mov_b64_e32 v[20:21], v[154:155]
	v_mov_b64_e32 v[22:23], v[156:157]
	v_mov_b64_e32 v[24:25], v[162:163]
	v_mov_b64_e32 v[26:27], v[164:165]
	v_mov_b64_e32 v[28:29], v[170:171]
	v_mov_b64_e32 v[30:31], v[172:173]
	v_mov_b64_e32 v[92:93], v[150:151]
	v_mov_b64_e32 v[94:95], v[152:153]
	v_mov_b64_e32 v[72:73], v[158:159]
	v_mov_b64_e32 v[74:75], v[160:161]
	v_mov_b64_e32 v[64:65], v[166:167]
	v_mov_b64_e32 v[66:67], v[168:169]
	v_mov_b64_e32 v[68:69], v[174:175]
	v_mov_b64_e32 v[70:71], v[176:177]
	s_cmp_lt_u32 s36, 31
	s_cbranch_scc0 .Lp8_compute
	v_lshl_add_u64 v[178:179], v[134:135], 0, v[130:131]
	v_add_co_u32_e32 v178, vcc, 0xb000, v178
	s_nop 1
	v_addc_co_u32_e32 v179, vcc, 0, v179, vcc
	s_cmp_lt_u32 s36, 27
	s_cselect_b64 s[0:1], -1, 0
	s_or_b64 s[0:1], s[0:1], s[34:35]
	v_add_co_u32_e32 v180, vcc, 0x12c02000, v178
	s_nop 1
	v_addc_co_u32_e32 v181, vcc, 0, v179, vcc
	global_load_dwordx4 v[146:149], v[180:181], off offset:3072
	v_add_co_u32_e32 v180, vcc, 0x12c04000, v178
	s_nop 1
	v_addc_co_u32_e32 v181, vcc, 0, v179, vcc
	global_load_dwordx4 v[150:153], v[180:181], off offset:512
	v_add_co_u32_e32 v180, vcc, 0x12c05000, v178
	s_nop 1
	v_addc_co_u32_e32 v181, vcc, 0, v179, vcc
	global_load_dwordx4 v[154:157], v[180:181], off offset:2048
	v_add_co_u32_e32 v180, vcc, 0x12c06000, v178
	s_nop 1
	v_addc_co_u32_e32 v181, vcc, 0, v179, vcc
	global_load_dwordx4 v[158:161], v[180:181], off offset:3584
	v_add_co_u32_e32 v180, vcc, 0x12c08000, v178
	s_nop 1
	v_addc_co_u32_e32 v181, vcc, 0, v179, vcc
	global_load_dwordx4 v[162:165], v[180:181], off offset:1024
	v_add_co_u32_e32 v180, vcc, 0x12c09000, v178
	s_nop 1
	v_addc_co_u32_e32 v181, vcc, 0, v179, vcc
	global_load_dwordx4 v[166:169], v[180:181], off offset:2560
	v_mov_b32_e32 v170, v12
	v_mov_b32_e32 v171, v12
	v_mov_b32_e32 v172, v12
	v_mov_b32_e32 v173, v12
	v_mov_b32_e32 v174, v12
	v_mov_b32_e32 v175, v12
	v_mov_b32_e32 v176, v12
	v_mov_b32_e32 v177, v12
	s_and_saveexec_b64 s[38:39], s[0:1]
	s_cbranch_execz .Lp8_skipB
	v_add_co_u32_e32 v180, vcc, 0x12c0b000, v178
	s_nop 1
	v_addc_co_u32_e32 v181, vcc, 0, v179, vcc
	global_load_dwordx4 v[170:173], v[180:181], off
	v_add_co_u32_e32 v180, vcc, 0x12c0c000, v178
	s_nop 1
	v_addc_co_u32_e32 v181, vcc, 0, v179, vcc
	global_load_dwordx4 v[174:177], v[180:181], off offset:1536
.Lp8_skipB:
	s_mov_b64 exec, s[38:39]
	s_branch .Lp8_compute
